# grid barrier at 12 of 13 seams replaced by a monotonic-counter barrier (non-returning arrive, release wait before arrive, acquire wait after); first seam keeps the cooperative-groups protocol and publ
# speedup vs baseline: 1.0411x; 1.0172x over previous
; #define PG8_LAS __attribute__((address_space(3)))
; __global__ void __launch_bounds__(512, 2) mega(Params p) {
;     extern __shared__ __attribute__((aligned(16))) unsigned char smem[];
;     cg::grid_group grid = cg::this_grid();
;     const int lo = p.ph_lo, hi = p.ph_hi;
;     ...
;     unsigned long long tp0 = (PROBE_PH >= 0) ? __builtin_amdgcn_s_memrealtime() : 0ull, tp1 = 0;
;     unsigned char* ws = p.ws;
;     PG8_LAS unsigned char* glds = (PG8_LAS unsigned char*)smem;
;     if (IN(0)) for (int rep_ = 0; rep_ < 1 + (REP_MASK & 1); ++rep_) {
;         tconv(smem, p.in[2], 8192, 0, 8192, 2048, (u16*)(ws + OFF_W0IN), 2048);
_Z4mega6Params:
	s_mov_b32 s100, 0
	s_mov_b32 s70, s2
	s_mov_b64 s[16:17], s[0:1]
	s_load_dwordx2 s[88:89], s[0:1], 0x0
	s_nop 0
	s_load_dwordx16 s[0:15], s[16:17], 0x10
	s_add_u32 s68, s16, 0x160
	s_addc_u32 s69, s17, 0
	s_waitcnt lgkmcnt(0)
	v_writelane_b32 v251, s0, 0
	s_nop 1
	v_writelane_b32 v251, s1, 1
	v_writelane_b32 v251, s2, 2
	v_writelane_b32 v251, s3, 3
	v_writelane_b32 v251, s4, 4
	v_writelane_b32 v251, s5, 5
	v_writelane_b32 v251, s6, 6
	v_writelane_b32 v251, s7, 7
	v_writelane_b32 v251, s8, 8
	v_writelane_b32 v251, s9, 9
	v_writelane_b32 v251, s10, 10
	v_writelane_b32 v251, s11, 11
	v_writelane_b32 v251, s12, 12
	v_writelane_b32 v251, s13, 13
	v_writelane_b32 v251, s14, 14
	v_writelane_b32 v251, s15, 15
	s_load_dwordx16 s[72:87], s[16:17], 0x50
	s_load_dwordx4 s[64:67], s[16:17], 0x150
	s_load_dwordx16 s[0:15], s[16:17], 0x90
	s_waitcnt lgkmcnt(0)
	s_cmp_lt_i32 s66, 1
	v_writelane_b32 v251, s0, 16
	s_nop 1
	v_writelane_b32 v251, s1, 17
	v_writelane_b32 v251, s2, 18
	v_writelane_b32 v251, s3, 19
	v_writelane_b32 v251, s4, 20
	v_writelane_b32 v251, s5, 21
	v_writelane_b32 v251, s6, 22
	v_writelane_b32 v251, s7, 23
	v_writelane_b32 v251, s8, 24
	v_writelane_b32 v251, s9, 25
	v_writelane_b32 v251, s10, 26
	v_writelane_b32 v251, s11, 27
	v_writelane_b32 v251, s12, 28
	v_writelane_b32 v251, s13, 29
	v_writelane_b32 v251, s14, 30
	v_writelane_b32 v251, s15, 31
	v_writelane_b32 v251, s16, 32
	s_load_dword s62, s[16:17], 0x160
	s_cselect_b64 s[0:1], -1, 0
	s_cmp_gt_i32 s67, 0
	s_cselect_b64 s[2:3], -1, 0
	s_and_b64 s[0:1], s[0:1], s[2:3]
	s_andn2_b64 vcc, exec, s[0:1]
	v_writelane_b32 v251, s17, 33
	s_cbranch_vccnz .LBB0_25
	v_and_b32_e32 v1, 0x3ff, v0
	v_lshlrev_b32_e32 v14, 2, v1
	v_bfe_u32 v16, v0, 4, 6
	v_and_b32_e32 v2, 60, v14
	v_lshlrev_b32_e32 v15, 3, v1
	v_lshlrev_b32_e32 v10, 2, v2
	v_mul_u32_u24_e32 v2, 0x41, v16
	v_bfe_u32 v17, v0, 3, 7
	v_and_b32_e32 v19, 56, v15
	v_lshlrev_b32_e32 v2, 2, v2
	s_cmpk_gt_i32 s70, 0xfff
	v_mov_b32_e32 v11, 0
	v_add3_u32 v18, 0, v10, v2
	v_add3_u32 v20, 0, v2, v10
	v_lshl_add_u32 v21, v17, 2, 0
	v_mul_u32_u24_e32 v22, 0x104, v19
	s_cbranch_scc1 .LBB0_8
	s_add_u32 s2, s64, 0x1c000000
	s_addc_u32 s3, s65, 0
	s_ashr_i32 s4, s70, 31
	s_lshr_b32 s4, s4, 25
	s_add_i32 s4, s70, s4
	s_ashr_i32 s5, s4, 7
	v_lshl_or_b32 v2, s5, 6, v16
	s_and_b32 s4, s4, 0x3ffff80
	v_ashrrev_i32_e32 v3, 31, v2
	v_readlane_b32 s8, v251, 0
	s_sub_i32 s4, s70, s4
	v_lshlrev_b64 v[2:3], 15, v[2:3]
	v_readlane_b32 s9, v251, 1
	s_lshl_b32 s4, s4, 6
	s_ashr_i32 s5, s4, 31
	v_lshl_add_u64 v[2:3], s[8:9], 0, v[2:3]
	v_lshl_add_u64 v[2:3], s[4:5], 2, v[2:3]
	v_lshl_add_u64 v[2:3], v[2:3], 0, v[10:11]
	s_mov_b32 s4, 0x100000
	v_add_co_u32_e32 v6, vcc, s4, v2
	v_readlane_b32 s12, v251, 4
	s_nop 0
	v_addc_co_u32_e32 v7, vcc, 0, v3, vcc
	global_load_dwordx4 v[2:5], v[2:3], off nt
	s_nop 0
	global_load_dwordx4 v[6:9], v[6:7], off nt
	v_add_u32_e32 v25, v21, v22
	s_lshl_b32 s9, s70, 6
	s_waitcnt lgkmcnt(0)
	s_lshl_b32 s8, s62, 6
	v_add_u32_e32 v23, 0x2080, v20
	v_add_u32_e32 v24, 0x2088, v20
	v_lshlrev_b32_e32 v12, 1, v19
	v_add_u32_e32 v26, 0x400, v25
	v_mov_b32_e32 v13, v11
	s_mov_b32 s12, s70
	v_readlane_b32 s10, v251, 2
	v_readlane_b32 s11, v251, 3
	v_readlane_b32 s13, v251, 5
	v_readlane_b32 s14, v251, 6
	v_readlane_b32 s15, v251, 7
	v_readlane_b32 s16, v251, 8
	v_readlane_b32 s17, v251, 9
	v_readlane_b32 s18, v251, 10
	v_readlane_b32 s19, v251, 11
	v_readlane_b32 s20, v251, 12
	v_readlane_b32 s21, v251, 13
	v_readlane_b32 s22, v251, 14
	v_readlane_b32 s23, v251, 15
	s_branch .LBB0_4

; #define PG8_LAS __attribute__((address_space(3)))
; #define SEAM(k) do { if (IN(k) && IN((k) + 1)) grid.sync(); if (PROBE_PH >= 0) { const unsigned long long tn_ = __builtin_amdgcn_s_memrealtime(); if ((PROBE_PH >> (k)) & 1) tp1 += tn_ - tp0; tp0 = tn_; } } while (0)
; __global__ void __launch_bounds__(512, 2) mega(Params p) {
;     ...
;     cg::grid_group grid = cg::this_grid();
;     const int lo = p.ph_lo, hi = p.ph_hi;
;     ...
;     unsigned long long tp0 = (PROBE_PH >= 0) ? __builtin_amdgcn_s_memrealtime() : 0ull, tp1 = 0;
;     unsigned char* ws = p.ws;
;     PG8_LAS unsigned char* glds = (PG8_LAS unsigned char*)smem;
;     if (IN(0)) for (int rep_ = 0; rep_ < 1 + (REP_MASK & 1); ++rep_) {
;         tconv(smem, p.in[2], 8192, 0, 8192, 2048, (u16*)(ws + OFF_W0IN), 2048);
;         tconv(smem, p.in[21], 2048, 0, 2048, 4096, (u16*)(ws + OFF_W0OUT), 4096);
;         prep_small(p);
;         rows_phase<0>(p);
;     }
;     SEAM(0);
.LBB0_25:
	s_cmp_gt_i32 s67, 1
	s_cselect_b64 s[2:3], -1, 0
	s_and_b64 s[0:1], s[0:1], s[2:3]
	s_andn2_b64 vcc, exec, s[0:1]
	s_cbranch_vccnz .LBB0_37
	v_and_b32_e32 v1, 0x3fffffff, v0
	v_cmp_eq_u32_e32 vcc, 0, v1
	s_waitcnt lgkmcnt(0)
	s_barrier
	s_and_saveexec_b64 s[0:1], vcc
	s_cbranch_execz .LBB0_36
	buffer_wbl2 sc1
	s_waitcnt vmcnt(0)
	s_load_dwordx2 s[4:5], s[68:69], 0x58
	v_mov_b32_e32 v3, 0
	s_mov_b64 s[6:7], exec
	v_mbcnt_lo_u32_b32 v2, s6, 0
	v_mbcnt_hi_u32_b32 v2, s7, v2
	s_waitcnt lgkmcnt(0)
	s_cmp_lg_u32 s70, 0
	s_cbranch_scc1 .Lfs_boot_skip
	global_store_dword v3, v3, s[4:5] offset:36 sc0 sc1
	s_waitcnt vmcnt(0)
.Lfs_boot_skip:
	global_load_dword v1, v3, s[4:5] offset:40
	v_cmp_eq_u32_e32 vcc, 0, v2
	s_and_saveexec_b64 s[8:9], vcc
	s_cbranch_execz .LBB0_29
	s_bcnt1_i32_b64 s6, s[6:7]
	v_mov_b32_e32 v4, s6
	global_atomic_add v4, v3, v4, s[4:5] offset:32 sc0

; #define SEAM(k) do { if (IN(k) && IN((k) + 1)) grid.sync(); if (PROBE_PH >= 0) { const unsigned long long tn_ = __builtin_amdgcn_s_memrealtime(); if ((PROBE_PH >> (k)) & 1) tp1 += tn_ - tp0; tp0 = tn_; } } while (0)
; __global__ void __launch_bounds__(512, 2) mega(Params p) {
;     ...
;     SEAM(1);
.LBB0_284:
	s_cmp_gt_i32 s67, 2
	s_cselect_b64 s[2:3], -1, 0
	s_and_b64 s[0:1], s[0:1], s[2:3]
	s_andn2_b64 vcc, exec, s[0:1]
	s_cbranch_vccnz .LBB0_296
	v_and_b32_e32 v1, 0x3fffffff, v0
	v_cmp_eq_u32_e32 vcc, 0, v1
	s_waitcnt vmcnt(0) lgkmcnt(0)
	s_barrier
	s_and_saveexec_b64 s[0:1], vcc
	s_cbranch_execz .LBB0_295
	buffer_wbl2 sc1
	s_load_dwordx2 s[4:5], s[68:69], 0x58
	v_mov_b32_e32 v3, 0
	v_mov_b32_e32 v1, 1
	s_waitcnt vmcnt(0) lgkmcnt(0)
	s_load_dword s101, s[4:5], 0x28
	global_atomic_add v3, v1, s[4:5] offset:36
	s_waitcnt lgkmcnt(0)
	s_add_u32 s100, s100, s101
	s_mov_b64 s[6:7], 0
.Lfs_poll_2:
	global_load_dword v2, v3, s[4:5] offset:36 sc1
	s_waitcnt vmcnt(0)
	v_subrev_u32_e32 v2, s100, v2
	v_cmp_le_i32_e32 vcc, 0, v2
	s_or_b64 s[6:7], vcc, s[6:7]
	s_andn2_b64 exec, exec, s[6:7]
	s_cbranch_execz .Lfs_done_2
	s_sleep 2
	s_branch .Lfs_poll_2
.Lfs_done_2:
	buffer_inv sc1
	s_waitcnt vmcnt(0)

; #define SEAM(k) do { if (IN(k) && IN((k) + 1)) grid.sync(); if (PROBE_PH >= 0) { const unsigned long long tn_ = __builtin_amdgcn_s_memrealtime(); if ((PROBE_PH >> (k)) & 1) tp1 += tn_ - tp0; tp0 = tn_; } } while (0)
; __global__ void __launch_bounds__(512, 2) mega(Params p) {
;     ...
;     SEAM(2);
.LBB0_359:
	s_cmp_gt_i32 s67, 3
	s_cselect_b64 s[0:1], -1, 0
	s_and_b64 s[2:3], s[8:9], s[0:1]
	s_andn2_b64 vcc, exec, s[2:3]
	s_cbranch_vccnz .LBB0_371
	v_and_b32_e32 v1, 0x3fffffff, v0
	v_cmp_eq_u32_e32 vcc, 0, v1
	s_waitcnt vmcnt(0) lgkmcnt(0)
	s_barrier
	s_and_saveexec_b64 s[2:3], vcc
	s_cbranch_execz .LBB0_370
	buffer_wbl2 sc1
	s_load_dwordx2 s[4:5], s[68:69], 0x58
	v_mov_b32_e32 v3, 0
	v_mov_b32_e32 v1, 1
	s_waitcnt vmcnt(0) lgkmcnt(0)
	s_load_dword s101, s[4:5], 0x28
	global_atomic_add v3, v1, s[4:5] offset:36
	s_waitcnt lgkmcnt(0)
	s_add_u32 s100, s100, s101
	s_mov_b64 s[6:7], 0

; #define SEAM(k) do { if (IN(k) && IN((k) + 1)) grid.sync(); if (PROBE_PH >= 0) { const unsigned long long tn_ = __builtin_amdgcn_s_memrealtime(); if ((PROBE_PH >> (k)) & 1) tp1 += tn_ - tp0; tp0 = tn_; } } while (0)
; __global__ void __launch_bounds__(512, 2) mega(Params p) {
;     ...
;     SEAM(3);
.LBB0_399:
	s_cmp_gt_i32 s67, 4
	s_cselect_b64 s[2:3], -1, 0
	s_and_b64 s[0:1], s[0:1], s[2:3]
	s_andn2_b64 vcc, exec, s[0:1]
	s_cbranch_vccnz .LBB0_411
	v_and_b32_e32 v1, 0x3fffffff, v0
	v_cmp_eq_u32_e32 vcc, 0, v1
	s_waitcnt vmcnt(0) lgkmcnt(0)
	s_barrier
	s_and_saveexec_b64 s[0:1], vcc
	s_cbranch_execz .LBB0_410
	buffer_wbl2 sc1
	s_load_dwordx2 s[4:5], s[68:69], 0x58
	v_mov_b32_e32 v3, 0
	v_mov_b32_e32 v1, 1
	s_waitcnt vmcnt(0) lgkmcnt(0)
	s_load_dword s101, s[4:5], 0x28
	global_atomic_add v3, v1, s[4:5] offset:36
	s_waitcnt lgkmcnt(0)
	s_add_u32 s100, s100, s101
	s_mov_b64 s[6:7], 0

; __device__ __forceinline__ float bflo(unsigned w) { return __uint_as_float(w << 16); }
; __device__ __forceinline__ float bfhi(unsigned w) { return __uint_as_float(w & 0xffff0000u); }
; __device__ void mlstm2_phase(const Params& p, unsigned char* smem) {
;     ...
;         for (int chunk = 0; chunk < 32; ++chunk) {
;             const int row0 = b * SEQL + chunk * 128, cu = bh_ * 32 + chunk;
; #pragma unroll
;             for (int i = 0; i < 8; ++i) { const int idx = tid + 512 * i, r = idx >> 5, cc = (idx & 31) * 8;
;                 *(u32x4*)(Ks + r * 264 + cc) = *(const u32x4*)(KX + (size_t)(row0 + r) * 2048 + 256 * h + cc); }
;             bf16x8 qf[8];
; #pragma unroll
;             for (int ks = 0; ks < 8; ++ks) qf[ks] = *(const bf16x8*)(Q + (size_t)(row0 + 16 * wave + l15) * 2048 + 256 * h + 32 * ks + 8 * lq);
;             float vv[2][4];
; #pragma unroll
;             for (int i = 0; i < 2; ++i) { const int t = (tid + 512 * i) >> 3; const u32x2 raw = *(const u32x2*)(XM + (size_t)(row0 + t) * 2048 + vc);
;                 const float x0 = bflo(raw.x), x1 = bfhi(raw.x), x2 = bflo(raw.y), x3 = bfhi(raw.y);
; #pragma unroll
;                 for (int jj = 0; jj < 4; ++jj) vv[i][jj] = x0 * wvp[jj] + x1 * wvp[4 + jj] + x2 * wvp[8 + jj] + x3 * wvp[12 + jj]; }
;             float m_new = 0.f;
;             const float* G = (const float*)(p.ws + OFF_G);
;             if (wave == 0) {
;                 const float m_prev = gS[1];
;                 const int t0 = 2 * lane;
;                 const float ig0 = G[(size_t)(row0 + t0) * 16 + h], fg0 = G[(size_t)(row0 + t0) * 16 + 8 + h];
;                 const float ig1 = G[(size_t)(row0 + t0 + 1) * 16 + h], fg1 = G[(size_t)(row0 + t0 + 1) * 16 + 8 + h];
.LBB0_423:
	s_mul_i32 s30, s79, 12
	v_lshl_add_u32 v88, v112, 2, s30
	global_load_dwordx2 v[82:83], v88, s[98:99]
	global_load_dwordx2 v[84:85], v88, s[98:99] offset:512
	global_load_dwordx2 v[86:87], v88, s[98:99] offset:1024
	v_add_u32_e32 v30, s79, v235
	v_ashrrev_i32_e32 v31, 31, v30
	v_lshlrev_b64 v[26:27], 12, v[30:31]
	v_lshl_add_u64 v[26:27], v[102:103], 0, v[26:27]
	global_load_dwordx4 v[26:29], v[26:27], off
	v_add_u32_e32 v32, s79, v238
	v_ashrrev_i32_e32 v33, 31, v32
	v_lshlrev_b64 v[32:33], 12, v[32:33]
	v_lshl_add_u64 v[32:33], v[102:103], 0, v[32:33]
	global_load_dwordx4 v[32:35], v[32:33], off
	v_add_u32_e32 v36, 32, v30
	v_ashrrev_i32_e32 v37, 31, v36
	v_lshlrev_b64 v[36:37], 12, v[36:37]
	v_lshl_add_u64 v[36:37], v[102:103], 0, v[36:37]
	global_load_dwordx4 v[36:39], v[36:37], off
	v_add_u32_e32 v40, s79, v237
	v_ashrrev_i32_e32 v41, 31, v40
	v_lshlrev_b64 v[40:41], 12, v[40:41]
	v_lshl_add_u64 v[40:41], v[102:103], 0, v[40:41]
	global_load_dwordx4 v[40:43], v[40:41], off
	v_add_u32_e32 v44, 64, v30
	v_ashrrev_i32_e32 v45, 31, v44
	v_lshlrev_b64 v[44:45], 12, v[44:45]
	v_lshl_add_u64 v[44:45], v[102:103], 0, v[44:45]
	global_load_dwordx4 v[44:47], v[44:45], off
	v_add_u32_e32 v48, s79, v236
	v_ashrrev_i32_e32 v49, 31, v48
	v_lshlrev_b64 v[48:49], 12, v[48:49]
	v_lshl_add_u64 v[48:49], v[102:103], 0, v[48:49]
	global_load_dwordx4 v[48:51], v[48:49], off
	v_add_u32_e32 v52, 0x60, v30
	v_ashrrev_i32_e32 v53, 31, v52
	v_lshlrev_b64 v[52:53], 12, v[52:53]
	v_lshl_add_u64 v[52:53], v[102:103], 0, v[52:53]
	global_load_dwordx4 v[52:55], v[52:53], off
	v_add_u32_e32 v60, s79, v234
	v_ashrrev_i32_e32 v61, 31, v60
	v_lshlrev_b64 v[60:61], 12, v[60:61]
	v_lshl_add_u64 v[60:61], v[102:103], 0, v[60:61]
	global_load_dwordx4 v[60:63], v[60:61], off
	v_add_u32_e32 v58, s79, v232
	v_ashrrev_i32_e32 v59, 31, v58
	v_lshlrev_b64 v[58:59], 12, v[58:59]
	v_lshl_add_u64 v[58:59], v[106:107], 0, v[58:59]
	v_add_u32_e32 v74, s79, v231
	v_ashrrev_i32_e32 v75, 31, v74
	v_lshlrev_b64 v[74:75], 12, v[74:75]
	v_lshl_add_u64 v[74:75], v[106:107], 0, v[74:75]
	s_andn2_b64 vcc, exec, s[84:85]
	v_mov_b32_e32 v78, 0
	s_waitcnt vmcnt(7)
	ds_write_b128 v213, v[26:29]
	s_waitcnt vmcnt(6)
	ds_write_b128 v214, v[32:35]
	s_waitcnt vmcnt(5)
	ds_write_b128 v213, v[36:39] offset:16896
	s_waitcnt vmcnt(4)
	ds_write_b128 v215, v[40:43]
	s_waitcnt vmcnt(3)
	ds_write_b128 v213, v[44:47] offset:33792
	s_waitcnt vmcnt(2)
	ds_write_b128 v216, v[48:51]
	s_waitcnt vmcnt(1)
	ds_write_b128 v213, v[52:55] offset:50688
	s_waitcnt vmcnt(0)
	ds_write_b128 v217, v[60:63]
	v_add_u32_e32 v26, s79, v233
	v_ashrrev_i32_e32 v27, 31, v26
	v_lshlrev_b64 v[26:27], 12, v[26:27]
	v_lshl_add_u64 v[26:27], v[104:105], 0, v[26:27]
	global_load_dwordx4 v[54:57], v[26:27], off
	global_load_dwordx4 v[50:53], v[26:27], off offset:64
	global_load_dwordx4 v[46:49], v[26:27], off offset:128
	global_load_dwordx4 v[42:45], v[26:27], off offset:192
	global_load_dwordx4 v[38:41], v[26:27], off offset:256
	global_load_dwordx4 v[34:37], v[26:27], off offset:320
	global_load_dwordx4 v[30:33], v[26:27], off offset:384
	s_nop 0
	global_load_dwordx4 v[26:29], v[26:27], off offset:448
	s_nop 0
	global_load_dwordx2 v[76:77], v[58:59], off
	s_nop 0
	global_load_dwordx4 v[58:61], v[100:101], off offset:48
	global_load_dwordx4 v[62:65], v[100:101], off offset:32
	global_load_dwordx4 v[70:73], v[100:101], off offset:16
	global_load_dwordx4 v[66:69], v[100:101], off
	s_nop 0
	global_load_dwordx2 v[74:75], v[74:75], off
	s_cbranch_vccnz .LBB0_427
	v_mov_b32_e32 v78, s33
	ds_read_b32 v80, v78
	s_waitcnt vmcnt(0) lgkmcnt(0)
	ds_bpermute_b32 v81, v227, v83
	v_max_f32_e32 v88, v87, v87
	v_max_f32_e32 v78, v80, v80
	v_max_f32_e32 v79, v86, v78
	v_max_f32_e32 v99, v88, v78
	v_sub_f32_e32 v88, v86, v79
	v_sub_f32_e32 v89, v87, v99
	v_mul_f32_e32 v88, 0x3fb8aa3b, v88
	v_mul_f32_e32 v89, 0x3fb8aa3b, v89
	v_exp_f32_e32 v88, v88
	v_exp_f32_e32 v89, v89
	ds_write_b64 v113, v[88:89]
	ds_write_b64 v114, v[86:87]
	ds_write_b64 v115, v[84:85]
	v_sub_f32_e32 v86, v80, v79
	v_add_f32_e32 v79, v82, v79
	ds_bpermute_b32 v78, v227, v99
	v_mul_f32_e32 v79, 0xbfb8aa3b, v79
	v_exp_f32_e32 v82, v79
	v_add_f32_e32 v79, v83, v99
	v_mul_f32_e32 v79, 0xbfb8aa3b, v79
	v_exp_f32_e32 v83, v79
	s_waitcnt lgkmcnt(0)
	v_sub_f32_e32 v79, v84, v78
	v_mul_f32_e32 v79, 0x3fb8aa3b, v79
	v_sub_f32_e32 v87, v80, v99
	ds_write_b64 v117, v[82:83]
	v_exp_f32_e32 v82, v79
	v_sub_f32_e32 v79, v85, v78
	v_mul_f32_e32 v86, 0x3fb8aa3b, v86
	v_mul_f32_e32 v87, 0x3fb8aa3b, v87
	v_mul_f32_e32 v79, 0x3fb8aa3b, v79
	v_exp_f32_e32 v86, v86
	v_exp_f32_e32 v87, v87
	v_exp_f32_e32 v83, v79
	ds_write_b64 v116, v[86:87]
	ds_write_b64 v118, v[82:83]
	s_and_saveexec_b64 s[52:53], s[4:5]
	s_cbranch_execz .LBB0_426
	v_sub_f32_e32 v79, v80, v78
	v_mul_f32_e32 v79, 0x3fb8aa3b, v79
	v_exp_f32_e32 v79, v79
	v_mov_b32_e32 v80, s91
	ds_write_b32 v80, v79

; #define SEAM(k) do { if (IN(k) && IN((k) + 1)) grid.sync(); if (PROBE_PH >= 0) { const unsigned long long tn_ = __builtin_amdgcn_s_memrealtime(); if ((PROBE_PH >> (k)) & 1) tp1 += tn_ - tp0; tp0 = tn_; } } while (0)
; __global__ void __launch_bounds__(512, 2) mega(Params p) {
;     ...
;     SEAM(4);
.LBB0_578:
	s_cmp_gt_i32 s67, 5
	v_readlane_b32 s2, v251, 34
	s_cselect_b64 s[0:1], -1, 0
	v_readlane_b32 s3, v251, 35
	s_and_b64 s[2:3], s[2:3], s[0:1]
	s_andn2_b64 vcc, exec, s[2:3]
	s_cbranch_vccnz .LBB0_590
	v_and_b32_e32 v1, 0x3fffffff, v0
	v_cmp_eq_u32_e32 vcc, 0, v1
	s_waitcnt vmcnt(0) lgkmcnt(0)
	s_barrier
	s_and_saveexec_b64 s[2:3], vcc
	s_cbranch_execz .LBB0_589
	buffer_wbl2 sc1
	s_load_dwordx2 s[4:5], s[68:69], 0x58
	v_mov_b32_e32 v3, 0
	v_mov_b32_e32 v1, 1
	s_waitcnt vmcnt(0) lgkmcnt(0)
	s_load_dword s101, s[4:5], 0x28
	global_atomic_add v3, v1, s[4:5] offset:36
	s_waitcnt lgkmcnt(0)
	s_add_u32 s100, s100, s101
	s_mov_b64 s[6:7], 0

; #define SEAM(k) do { if (IN(k) && IN((k) + 1)) grid.sync(); if (PROBE_PH >= 0) { const unsigned long long tn_ = __builtin_amdgcn_s_memrealtime(); if ((PROBE_PH >> (k)) & 1) tp1 += tn_ - tp0; tp0 = tn_; } } while (0)
; __global__ void __launch_bounds__(512, 2) mega(Params p) {
;     ...
;     SEAM(5);
.LBB0_625:
	s_cmp_gt_i32 s67, 6
	s_cselect_b64 s[2:3], -1, 0
	s_and_b64 s[0:1], s[0:1], s[2:3]
	s_andn2_b64 vcc, exec, s[0:1]
	s_cbranch_vccnz .LBB0_637
	v_and_b32_e32 v1, 0x3fffffff, v0
	v_cmp_eq_u32_e32 vcc, 0, v1
	s_waitcnt vmcnt(0) lgkmcnt(0)
	s_barrier
	s_and_saveexec_b64 s[0:1], vcc
	s_cbranch_execz .LBB0_636
	buffer_wbl2 sc1
	s_load_dwordx2 s[4:5], s[68:69], 0x58
	v_mov_b32_e32 v3, 0
	v_mov_b32_e32 v1, 1
	s_waitcnt vmcnt(0) lgkmcnt(0)
	s_load_dword s101, s[4:5], 0x28
	global_atomic_add v3, v1, s[4:5] offset:36
	s_waitcnt lgkmcnt(0)
	s_add_u32 s100, s100, s101
	s_mov_b64 s[6:7], 0

; #define SEAM(k) do { if (IN(k) && IN((k) + 1)) grid.sync(); if (PROBE_PH >= 0) { const unsigned long long tn_ = __builtin_amdgcn_s_memrealtime(); if ((PROBE_PH >> (k)) & 1) tp1 += tn_ - tp0; tp0 = tn_; } } while (0)
; __global__ void __launch_bounds__(512, 2) mega(Params p) {
;     ...
;     SEAM(6);
.LBB0_658:
	v_readlane_b32 s2, v251, 32
	v_readlane_b32 s3, v251, 33
	s_waitcnt lgkmcnt(0)
	s_load_dwordx16 s[4:19], s[2:3], 0x110
	s_cmp_gt_i32 s67, 7
	s_cselect_b64 s[2:3], -1, 0
	s_and_b64 s[0:1], s[0:1], s[2:3]
	s_andn2_b64 vcc, exec, s[0:1]
	s_waitcnt lgkmcnt(0)
	v_writelane_b32 v250, s4, 5
	s_nop 1
	v_writelane_b32 v250, s5, 6
	v_writelane_b32 v250, s6, 7
	v_writelane_b32 v250, s7, 8
	v_writelane_b32 v250, s8, 9
	v_writelane_b32 v250, s9, 10
	v_writelane_b32 v250, s10, 11
	v_writelane_b32 v250, s11, 12
	v_writelane_b32 v250, s12, 13
	v_writelane_b32 v250, s13, 14
	v_writelane_b32 v250, s14, 15
	v_writelane_b32 v250, s15, 16
	v_writelane_b32 v250, s16, 17
	v_writelane_b32 v250, s17, 18
	v_writelane_b32 v250, s18, 19
	v_writelane_b32 v250, s19, 20
	s_cbranch_vccnz .LBB0_670
	v_and_b32_e32 v1, 0x3fffffff, v0
	v_cmp_eq_u32_e32 vcc, 0, v1
	s_waitcnt vmcnt(0)
	s_barrier
	s_and_saveexec_b64 s[0:1], vcc
	s_cbranch_execz .LBB0_669
	buffer_wbl2 sc1
	s_load_dwordx2 s[4:5], s[68:69], 0x58
	v_mov_b32_e32 v3, 0
	v_mov_b32_e32 v1, 1
	s_waitcnt vmcnt(0) lgkmcnt(0)
	s_load_dword s101, s[4:5], 0x28
	global_atomic_add v3, v1, s[4:5] offset:36
	s_waitcnt lgkmcnt(0)
	s_add_u32 s100, s100, s101
	s_mov_b64 s[6:7], 0

; #define SEAM(k) do { if (IN(k) && IN((k) + 1)) grid.sync(); if (PROBE_PH >= 0) { const unsigned long long tn_ = __builtin_amdgcn_s_memrealtime(); if ((PROBE_PH >> (k)) & 1) tp1 += tn_ - tp0; tp0 = tn_; } } while (0)
; __global__ void __launch_bounds__(512, 2) mega(Params p) {
;     ...
;     SEAM(7);
.LBB0_699:
	s_cmp_gt_i32 s67, 8
	s_cselect_b64 s[2:3], -1, 0
	s_and_b64 s[0:1], s[0:1], s[2:3]
	s_andn2_b64 vcc, exec, s[0:1]
	s_cbranch_vccnz .LBB0_711
	v_and_b32_e32 v1, 0x3fffffff, v0
	v_cmp_eq_u32_e32 vcc, 0, v1
	s_barrier
	s_and_saveexec_b64 s[0:1], vcc
	s_cbranch_execz .LBB0_710
	buffer_wbl2 sc1
	s_load_dwordx2 s[4:5], s[68:69], 0x58
	v_mov_b32_e32 v3, 0
	v_mov_b32_e32 v1, 1
	s_waitcnt vmcnt(0) lgkmcnt(0)
	s_load_dword s101, s[4:5], 0x28
	global_atomic_add v3, v1, s[4:5] offset:36
	s_waitcnt lgkmcnt(0)
	s_add_u32 s100, s100, s101
	s_mov_b64 s[6:7], 0

; #define SEAM(k) do { if (IN(k) && IN((k) + 1)) grid.sync(); if (PROBE_PH >= 0) { const unsigned long long tn_ = __builtin_amdgcn_s_memrealtime(); if ((PROBE_PH >> (k)) & 1) tp1 += tn_ - tp0; tp0 = tn_; } } while (0)
; __global__ void __launch_bounds__(512, 2) mega(Params p) {
;     ...
;     SEAM(8);
.LBB0_814:
	s_cmp_gt_i32 s67, 9
	s_cselect_b64 s[0:1], -1, 0
	s_and_b64 s[2:3], s[6:7], s[0:1]
	s_andn2_b64 vcc, exec, s[2:3]
	s_cbranch_vccnz .LBB0_826
	v_and_b32_e32 v1, 0x3fffffff, v0
	v_cmp_eq_u32_e32 vcc, 0, v1
	s_waitcnt vmcnt(0) lgkmcnt(0)
	s_barrier
	s_and_saveexec_b64 s[2:3], vcc
	s_cbranch_execz .LBB0_825
	buffer_wbl2 sc1
	s_load_dwordx2 s[4:5], s[68:69], 0x58
	v_mov_b32_e32 v3, 0
	v_mov_b32_e32 v1, 1
	s_waitcnt vmcnt(0) lgkmcnt(0)
	s_load_dword s101, s[4:5], 0x28
	global_atomic_add v3, v1, s[4:5] offset:36
	s_waitcnt lgkmcnt(0)
	s_add_u32 s100, s100, s101
	s_mov_b64 s[6:7], 0

; __global__ void __launch_bounds__(512, 2) mega(Params p) {
;     ...
;         ptanh_phase(p);
;         grid.sync();
;         { const unsigned long long tw_ = rwkv2_phase(p, smem); if (PROBE_ROLE >= 0) tp1 += tw_; }
.LBB0_832:
	s_or_b64 exec, exec, s[0:1]
	v_lshrrev_b32_e32 v1, 20, v0
	v_lshrrev_b32_e32 v2, 10, v0
	v_or_b32_e32 v1, v2, v1
	s_movk_i32 s0, 0x3ff
	v_and_or_b32 v1, v1, s0, v103
	v_cmp_eq_u32_e32 vcc, 0, v1
	s_waitcnt lgkmcnt(0)
	s_barrier
	s_and_saveexec_b64 s[0:1], vcc
	s_cbranch_execz .LBB0_842
	buffer_wbl2 sc1
	s_load_dwordx2 s[2:3], s[68:69], 0x58
	v_mov_b32_e32 v3, 0
	v_mov_b32_e32 v1, 1
	s_waitcnt vmcnt(0) lgkmcnt(0)
	s_load_dword s101, s[2:3], 0x28
	global_atomic_add v3, v1, s[2:3] offset:36
	s_waitcnt lgkmcnt(0)
	s_add_u32 s100, s100, s101
	s_mov_b64 s[4:5], 0
.Lfs_poll_10:
	global_load_dword v2, v3, s[2:3] offset:36 sc1
	s_waitcnt vmcnt(0)
	v_subrev_u32_e32 v2, s100, v2
	v_cmp_le_i32_e32 vcc, 0, v2
	s_or_b64 s[4:5], vcc, s[4:5]
	s_andn2_b64 exec, exec, s[4:5]
	s_cbranch_execz .Lfs_done_10
	s_sleep 2
	s_branch .Lfs_poll_10

; #define SEAM(k) do { if (IN(k) && IN((k) + 1)) grid.sync(); if (PROBE_PH >= 0) { const unsigned long long tn_ = __builtin_amdgcn_s_memrealtime(); if ((PROBE_PH >> (k)) & 1) tp1 += tn_ - tp0; tp0 = tn_; } } while (0)
; __global__ void __launch_bounds__(512, 2) mega(Params p) {
;     ...
;     SEAM(9);
.LBB0_1028:
	s_cmp_gt_i32 s67, 10
	v_readlane_b32 s2, v250, 45
	s_cselect_b64 s[0:1], -1, 0
	v_readlane_b32 s3, v250, 46
	s_and_b64 s[2:3], s[2:3], s[0:1]
	s_andn2_b64 vcc, exec, s[2:3]
	s_cbranch_vccnz .LBB0_1040
	v_and_b32_e32 v1, 0x3fffffff, v0
	v_cmp_eq_u32_e32 vcc, 0, v1
	s_waitcnt vmcnt(0) lgkmcnt(0)
	s_barrier
	s_and_saveexec_b64 s[2:3], vcc
	s_cbranch_execz .LBB0_1039
	buffer_wbl2 sc1
	s_load_dwordx2 s[4:5], s[68:69], 0x58
	v_mov_b32_e32 v3, 0
	v_mov_b32_e32 v1, 1
	s_waitcnt vmcnt(0) lgkmcnt(0)
	s_load_dword s101, s[4:5], 0x28
	global_atomic_add v3, v1, s[4:5] offset:36
	s_waitcnt lgkmcnt(0)
	s_add_u32 s100, s100, s101
	s_mov_b64 s[6:7], 0

; #define SEAM(k) do { if (IN(k) && IN((k) + 1)) grid.sync(); if (PROBE_PH >= 0) { const unsigned long long tn_ = __builtin_amdgcn_s_memrealtime(); if ((PROBE_PH >> (k)) & 1) tp1 += tn_ - tp0; tp0 = tn_; } } while (0)
; __global__ void __launch_bounds__(512, 2) mega(Params p) {
;     ...
;     SEAM(10);
.LBB0_1061:
	s_cmp_gt_i32 s67, 11
	s_cselect_b64 s[0:1], -1, 0
	s_and_b64 s[2:3], s[8:9], s[0:1]
	s_andn2_b64 vcc, exec, s[2:3]
	s_cbranch_vccnz .LBB0_1073
	v_and_b32_e32 v1, 0x3fffffff, v0
	v_cmp_eq_u32_e32 vcc, 0, v1
	s_waitcnt vmcnt(0) lgkmcnt(0)
	s_barrier
	s_and_saveexec_b64 s[2:3], vcc
	s_cbranch_execz .LBB0_1072
	buffer_wbl2 sc1
	s_load_dwordx2 s[4:5], s[68:69], 0x58
	v_mov_b32_e32 v3, 0
	v_mov_b32_e32 v1, 1
	s_waitcnt vmcnt(0) lgkmcnt(0)
	s_load_dword s101, s[4:5], 0x28
	global_atomic_add v3, v1, s[4:5] offset:36
	s_waitcnt lgkmcnt(0)
	s_add_u32 s100, s100, s101
	s_mov_b64 s[6:7], 0

; #define SEAM(k) do { if (IN(k) && IN((k) + 1)) grid.sync(); if (PROBE_PH >= 0) { const unsigned long long tn_ = __builtin_amdgcn_s_memrealtime(); if ((PROBE_PH >> (k)) & 1) tp1 += tn_ - tp0; tp0 = tn_; } } while (0)
; __global__ void __launch_bounds__(512, 2) mega(Params p) {
;     ...
;     SEAM(11);
.LBB0_1094:
	s_cmp_gt_i32 s67, 12
	s_cselect_b64 s[0:1], -1, 0
	s_and_b64 s[2:3], s[2:3], s[0:1]
	s_andn2_b64 vcc, exec, s[2:3]
	s_cbranch_vccnz .LBB0_1106
	v_and_b32_e32 v1, 0x3fffffff, v0
	v_cmp_eq_u32_e32 vcc, 0, v1
	s_waitcnt vmcnt(0) lgkmcnt(0)
	s_barrier
	s_and_saveexec_b64 s[2:3], vcc
	s_cbranch_execz .LBB0_1105
	buffer_wbl2 sc1
	s_load_dwordx2 s[4:5], s[68:69], 0x58
	v_mov_b32_e32 v3, 0
	v_mov_b32_e32 v1, 1
	s_waitcnt vmcnt(0) lgkmcnt(0)
	s_load_dword s101, s[4:5], 0x28
	global_atomic_add v3, v1, s[4:5] offset:36
	s_waitcnt lgkmcnt(0)
	s_add_u32 s100, s100, s101
	s_mov_b64 s[6:7], 0
